# XCD-locality item permutation in GLA/SSD pass phases (blocks of one XCD take the items that share q/k/B/C operands)
# speedup vs baseline: 1.1183x; 1.0158x over previous
.LBB0_413:
	s_or_b64 exec, exec, s[38:39]
	v_readlane_b32 s2, v254, 56
	s_cmpk_ge_i32 s2, 0x1e0
	s_cbranch_scc1 .Lperm_0
	s_and_b32 m0, s2, 7
	s_lshl_b32 m0, m0, 2
	s_bfe_u32 s98, s2, 0x20003
	s_add_i32 m0, m0, s98
	s_andn2_b32 s2, s2, 31
	s_or_b32 s2, s2, m0
.Lperm_0:
	s_cmpk_lt_i32 s2, 0x1f0
	s_cselect_b64 s[4:5], -1, 0
	v_writelane_b32 v255, s4, 12
	v_mov_b32_e32 v0, v190
	s_cmpk_gt_i32 s2, 0x1ef
	v_writelane_b32 v255, s5, 13
	s_waitcnt lgkmcnt(0)
	s_barrier
	s_cbranch_scc1 .LBB0_491
	v_lshlrev_b32_e32 v5, 3, v0
	v_and_b32_e32 v10, 56, v5
	v_readlane_b32 s2, v255, 6
	v_lshlrev_b32_e32 v120, 1, v10
	v_mov_b32_e32 v121, 0
	v_readlane_b32 s3, v255, 7
	v_and_b32_e32 v127, 15, v0
	v_bfe_u32 v1, v0, 4, 2
	v_lshl_add_u64 v[122:123], s[2:3], 0, v[120:121]
	v_readlane_b32 s2, v254, 60
	v_readlane_b32 s3, v254, 61
	v_mul_u32_u24_e32 v5, 0x48, v127
	v_lshlrev_b32_e32 v6, 4, v1
	v_ashrrev_i32_e32 v3, 6, v0
	v_lshl_add_u64 v[124:125], s[2:3], 0, v[120:121]
	v_lshl_add_u32 v126, v5, 1, v6
	s_movk_i32 s2, 0x1200
	v_lshlrev_b32_e32 v118, 5, v3
	v_lshlrev_b32_e32 v2, 2, v1
	v_mad_u64_u32 v[128:129], s[2:3], v3, s2, v[126:127]
	v_or_b32_e32 v4, v2, v118
	v_readlane_b32 s2, v255, 8
	v_ashrrev_i32_e32 v119, 31, v118
	v_readlane_b32 s3, v255, 9
	v_ashrrev_i32_e32 v5, 31, v4
	v_add_u32_e32 v1, 0x100, v0
	v_lshl_add_u64 v[8:9], v[118:119], 2, s[2:3]
	v_lshl_add_u64 v[4:5], v[4:5], 2, s[52:53]
	s_mov_b64 s[2:3], 0xc7d8000
	v_ashrrev_i32_e32 v134, 3, v0
	v_ashrrev_i32_e32 v136, 3, v1
	v_add_u32_e32 v1, 0x200, v0
	v_add_u32_e32 v0, 0x300, v0
	v_lshl_add_u64 v[132:133], v[4:5], 0, s[2:3]
	v_ashrrev_i32_e32 v138, 3, v1
	v_ashrrev_i32_e32 v140, 3, v0
	s_movk_i32 s2, 0x90
	v_mov_b32_e32 v7, v121
	v_mul_lo_u32 v0, v134, s2
	v_mul_lo_u32 v1, v136, s2
	v_mul_lo_u32 v3, v138, s2
	v_mul_lo_u32 v4, v140, s2
	s_add_u32 s18, s52, 0xd7d8000
	v_lshlrev_b32_e32 v142, 2, v2
	v_lshl_add_u64 v[130:131], v[8:9], 0, v[6:7]
	v_cmp_gt_u32_e32 vcc, 16, v10
	v_ashrrev_i32_e32 v135, 31, v134
	v_ashrrev_i32_e32 v137, 31, v136
	v_ashrrev_i32_e32 v139, 31, v138
	v_ashrrev_i32_e32 v141, 31, v140
	s_addc_u32 s19, s53, 0
	s_mov_b32 s5, 0
	v_mov_b32_e32 v144, v142
	v_mov_b32_e32 v145, v121
	v_add_u32_e32 v129, v120, v0
	v_add_u32_e32 v148, v120, v1
	v_add_u32_e32 v149, v120, v3
	v_add_u32_e32 v150, v120, v4
	v_readlane_b32 s20, v254, 56
	s_cmpk_ge_i32 s20, 0x1e0
	s_cbranch_scc1 .Lperm_1
	s_and_b32 m0, s20, 7
	s_lshl_b32 m0, m0, 2
	s_bfe_u32 s98, s20, 0x20003
	s_add_i32 m0, m0, s98
	s_andn2_b32 s20, s20, 31
	s_or_b32 s20, s20, m0
.Lperm_1:
	s_branch .LBB0_416

.LBB0_625:
	s_or_b64 exec, exec, s[38:39]
	s_waitcnt lgkmcnt(0)
	s_add_u32 s2, s52, 0xa510000
	s_addc_u32 s3, s53, 0
	v_writelane_b32 v255, s2, 17
	v_mov_b32_e32 v1, v190
	s_nop 0
	v_writelane_b32 v255, s3, 18
	s_add_u32 s2, s52, 0xc652000
	s_addc_u32 s3, s53, 0
	v_writelane_b32 v255, s2, 19
	s_barrier
	s_nop 0
	v_writelane_b32 v255, s3, 20
	v_readlane_b32 s2, v254, 56
	s_cmpk_ge_i32 s2, 0x1e0
	s_cbranch_scc1 .Lperm_2
	s_and_b32 m0, s2, 7
	s_lshl_b32 m0, m0, 2
	s_bfe_u32 s98, s2, 0x20003
	s_add_i32 m0, m0, s98
	s_andn2_b32 s2, s2, 31
	s_or_b32 s2, s2, m0
.Lperm_2:
	s_cmpk_lt_i32 s2, 0x280
	s_cselect_b64 s[4:5], -1, 0
	v_writelane_b32 v255, s4, 21
	s_cmpk_gt_i32 s2, 0x27f
	s_nop 0
	v_writelane_b32 v255, s5, 22
	v_writelane_b32 v255, s72, 23
	s_nop 1
	v_writelane_b32 v255, s73, 24
	v_writelane_b32 v255, s74, 25
	v_writelane_b32 v255, s75, 26
	v_writelane_b32 v255, s76, 27
	v_writelane_b32 v255, s77, 28
	v_writelane_b32 v255, s78, 29
	v_writelane_b32 v255, s79, 30
	v_writelane_b32 v255, s80, 31
	v_writelane_b32 v255, s81, 32
	v_writelane_b32 v255, s82, 33
	v_writelane_b32 v255, s83, 34
	v_writelane_b32 v255, s84, 35
	v_writelane_b32 v255, s85, 36
	v_writelane_b32 v255, s86, 37
	v_writelane_b32 v255, s87, 38
	v_readlane_b32 s87, v254, 57
	s_cbranch_scc1 .LBB0_755
	v_lshlrev_b32_e32 v0, 3, v1
	v_and_b32_e32 v12, 56, v0
	v_mov_b32_e32 v0, 0
	v_readlane_b32 s2, v255, 6
	v_and_b32_e32 v124, 15, v1
	v_lshlrev_b32_e32 v4, 1, v12
	v_mov_b32_e32 v5, v0
	v_readlane_b32 s3, v255, 7
	v_bfe_u32 v3, v1, 4, 2
	v_ashrrev_i32_e32 v9, 6, v1
	v_lshl_add_u64 v[130:131], s[2:3], 0, v[4:5]
	v_readlane_b32 s2, v254, 60
	v_mul_u32_u24_e32 v6, 0x48, v124
	v_lshlrev_b32_e32 v126, 5, v9
	v_readlane_b32 s3, v254, 61
	v_lshlrev_b32_e32 v13, 1, v6
	v_lshlrev_b32_e32 v6, 4, v3
	v_lshl_add_u64 v[132:133], s[2:3], 0, v[4:5]
	v_ashrrev_i32_e32 v127, 31, v126
	v_add_u32_e32 v134, v6, v13
	s_movk_i32 s2, 0x1200
	v_mad_u64_u32 v[136:137], s[2:3], v9, s2, v[134:135]
	v_lshl_add_u64 v[10:11], v[126:127], 2, s[84:85]
	v_mov_b32_e32 v7, v0
	v_lshl_add_u64 v[138:139], v[10:11], 0, v[6:7]
	s_movk_i32 s2, 0x1100
	v_mul_u32_u24_e32 v7, 0x88, v124
	v_lshlrev_b32_e32 v2, 2, v3
	v_lshlrev_b32_e32 v5, 3, v3
	v_mul_lo_u32 v3, v9, s2
	v_lshlrev_b32_e32 v7, 1, v7
	s_movk_i32 s2, 0xffc0
	v_add3_u32 v135, v3, v7, v6
	v_and_or_b32 v3, v1, s2, v5
	s_movk_i32 s2, 0x900
	v_ashrrev_i32_e32 v144, 3, v1
	s_movk_i32 s8, 0x90
	v_lshlrev_b32_e32 v8, 4, v124
	v_lshl_or_b32 v173, v9, 4, v2
	v_mul_lo_u32 v5, v9, s2
	v_mul_lo_u32 v9, v144, s8
	v_ashrrev_i32_e32 v189, 4, v1
	s_movk_i32 s9, 0x110
	v_add3_u32 v184, v5, v13, v6
	v_add_u32_e32 v5, 0x100, v1
	v_mad_u64_u32 v[152:153], s[6:7], v189, s9, v[8:9]
	v_ashrrev_i32_e32 v153, 4, v5
	v_add_u32_e32 v6, 0x200, v1
	v_mad_u64_u32 v[154:155], s[6:7], v153, s9, v[8:9]
	v_ashrrev_i32_e32 v155, 4, v6
	v_add_u32_e32 v7, 0x300, v1
	v_mad_u64_u32 v[156:157], s[6:7], v155, s9, v[8:9]
	v_ashrrev_i32_e32 v157, 4, v7
	v_mad_u64_u32 v[158:159], s[6:7], v157, s9, v[8:9]
	v_ashrrev_i32_e32 v146, 3, v5
	v_or_b32_e32 v5, 16, v124
	v_or_b32_e32 v159, 1, v173
	v_or_b32_e32 v192, 2, v173
	v_or_b32_e32 v193, 3, v173
	v_or_b32_e32 v13, 48, v124
	v_cmp_gt_i32_e64 s[14:15], v5, v173
	v_cmp_gt_i32_e64 s[16:17], v5, v159
	v_cmp_gt_i32_e64 s[18:19], v5, v192
	v_cmp_gt_i32_e64 s[20:21], v5, v193
	v_mbcnt_hi_u32_b32 v5, -1, v191
	v_ashrrev_i32_e32 v150, 3, v7
	v_or_b32_e32 v7, 32, v124
	v_cmp_gt_i32_e64 s[30:31], v13, v173
	v_cmp_gt_i32_e64 s[34:35], v13, v159
	v_cmp_gt_i32_e64 s[36:37], v13, v192
	v_cmp_gt_i32_e64 s[38:39], v13, v193
	v_and_b32_e32 v13, 64, v5
	v_cmp_gt_i32_e64 s[22:23], v7, v173
	v_cmp_gt_i32_e64 s[24:25], v7, v159
	v_cmp_gt_i32_e64 s[26:27], v7, v192
	v_cmp_gt_i32_e64 s[28:29], v7, v193
	v_xor_b32_e32 v7, 1, v5
	v_add_u32_e32 v13, 64, v13
	v_cmp_lt_i32_e32 vcc, v7, v13
	v_or_b32_e32 v128, v2, v126
	v_ashrrev_i32_e32 v148, 3, v6
	v_cndmask_b32_e32 v7, v5, v7, vcc
	v_lshlrev_b32_e32 v194, 2, v7
	v_xor_b32_e32 v7, 2, v5
	v_cmp_lt_i32_e32 vcc, v7, v13
	v_mov_b32_e32 v6, 0x1100
	v_mov_b32_e32 v8, 0x2200
	v_cndmask_b32_e32 v7, v5, v7, vcc
	v_lshlrev_b32_e32 v195, 2, v7
	v_xor_b32_e32 v7, 4, v5
	v_cmp_lt_i32_e32 vcc, v7, v13
	v_mov_b32_e32 v14, 0x3300
	v_readlane_b32 s40, v255, 15
	v_cndmask_b32_e32 v7, v5, v7, vcc
	v_lshlrev_b32_e32 v196, 2, v7
	v_xor_b32_e32 v7, 8, v5
	v_or_b32_e32 v142, 16, v128
	v_cmp_gt_u32_e64 s[4:5], 16, v12
	v_mul_lo_u32 v10, v146, s8
	v_mul_lo_u32 v11, v148, s8
	v_mul_lo_u32 v12, v150, s8
	v_mul_u32_u24_e32 v1, 0x110, v124
	v_mad_u32_u24 v6, v124, s9, v6
	v_mad_u32_u24 v8, v124, s9, v8
	v_mad_u32_u24 v14, v124, s9, v14
	v_cmp_lt_i32_e32 vcc, v7, v13
	v_lshl_add_u32 v137, v124, 7, v134
	v_ashrrev_i32_e32 v129, 31, v128
	v_readlane_b32 s41, v255, 16
	v_ashrrev_i32_e32 v143, 31, v142
	v_lshlrev_b32_e32 v15, 1, v124
	v_mul_lo_u32 v16, v173, s8
	v_cndmask_b32_e32 v5, v5, v7, vcc
	v_lshlrev_b32_e32 v162, 2, v2
	v_add_u32_e32 v198, v4, v9
	v_add_u32_e32 v199, v4, v10
	v_add_u32_e32 v200, v4, v11
	v_add_u32_e32 v201, v4, v12
	v_add_u32_e32 v1, v3, v1
	v_add_u32_e32 v2, v3, v6
	v_add_u32_e32 v4, v3, v8
	v_add_u32_e32 v3, v3, v14
	v_lshlrev_b32_e32 v125, 3, v124
	v_add_u32_e32 v185, 0xf400, v137
	v_add_u32_e32 v186, 0xf440, v137
	v_add_u32_e32 v187, 0xf480, v137
	v_add_u32_e32 v188, 0xf4c0, v137
	s_mov_b32 s53, 0
	v_cmp_eq_u32_e64 s[2:3], 0, v124
	v_lshl_add_u64 v[140:141], v[128:129], 2, s[40:41]
	v_ashrrev_i32_e32 v145, 31, v144
	v_ashrrev_i32_e32 v147, 31, v146
	v_ashrrev_i32_e32 v149, 31, v148
	v_ashrrev_i32_e32 v151, 31, v150
	v_cmp_gt_i32_e64 s[6:7], v124, v173
	v_cmp_gt_i32_e64 s[8:9], v124, v159
	v_cmp_gt_i32_e64 s[10:11], v124, v192
	v_cmp_gt_i32_e64 s[12:13], v124, v193
	v_lshlrev_b32_e32 v197, 2, v5
	v_lshl_add_u64 v[160:161], v[142:143], 2, s[40:41]
	v_lshlrev_b32_e32 v164, 1, v124
	s_movk_i32 s33, 0x7fff
	v_add_u32_e32 v202, v15, v16
	v_mov_b32_e32 v203, 1
	v_add_u32_e32 v204, 0xf000, v1
	v_add_u32_e32 v205, 0xf000, v2
	v_add_u32_e32 v206, 0xf000, v4
	v_add_u32_e32 v207, 0xf000, v3
	v_readlane_b32 s74, v254, 56
	s_cmpk_ge_i32 s74, 0x1e0
	s_cbranch_scc1 .Lperm_3
	s_and_b32 m0, s74, 7
	s_lshl_b32 m0, m0, 2
	s_bfe_u32 s98, s74, 0x20003
	s_add_i32 m0, m0, s98
	s_andn2_b32 s74, s74, 31
	s_or_b32 s74, s74, m0

.LBB0_1506:
	s_or_b64 exec, exec, s[0:1]
	s_add_u32 s0, s52, 0xf0c8000
	s_addc_u32 s1, s53, 0
	v_readlane_b32 s2, v254, 56
	s_cmpk_ge_i32 s2, 0x1e0
	s_cbranch_scc1 .Lperm_6
	s_and_b32 m0, s2, 7
	s_lshl_b32 m0, m0, 2
	s_bfe_u32 s98, s2, 0x20003
	s_add_i32 m0, m0, s98
	s_andn2_b32 s2, s2, 31
	s_or_b32 s2, s2, m0
.Lperm_6:
	v_mov_b32_e32 v61, v190
	s_cmpk_gt_i32 s2, 0x1df
	s_waitcnt lgkmcnt(0)
	s_barrier
	s_cbranch_scc1 .LBB0_1538
	v_ashrrev_i32_e32 v1, 6, v61
	v_lshlrev_b32_e32 v0, 5, v1
	v_lshrrev_b32_e32 v2, 2, v61
	v_and_or_b32 v2, v2, 12, v0
	v_lshlrev_b32_e32 v0, 3, v61
	v_and_b32_e32 v71, 56, v0
	v_mov_b32_e32 v0, 0
	v_and_b32_e32 v60, 15, v61
	v_lshlrev_b32_e32 v4, 1, v71
	v_mov_b32_e32 v5, v0
	v_lshl_add_u64 v[62:63], s[40:41], 0, v[4:5]
	v_and_b32_e32 v3, 48, v61
	v_mul_u32_u24_e32 v5, 0x48, v60
	v_and_b32_e32 v65, 63, v61
	v_lshl_add_u32 v64, v5, 1, v3
	s_movk_i32 s2, 0x1200
	v_mad_u64_u32 v[66:67], s[2:3], v1, s2, v[64:65]
	v_lshlrev_b32_e32 v1, 2, v65
	v_or_b32_e32 v75, 0x13c00, v1
	v_or_b32_e32 v112, 0x13d00, v1
	v_ashrrev_i32_e32 v3, 31, v2
	v_add_u32_e32 v1, 0x100, v61
	v_lshl_add_u64 v[2:3], v[2:3], 2, s[52:53]
	s_mov_b64 s[8:9], 0xe0c8000
	v_ashrrev_i32_e32 v76, 3, v61
	v_ashrrev_i32_e32 v78, 3, v1
	v_lshl_add_u64 v[68:69], v[2:3], 0, s[8:9]
	v_ashrrev_i32_e32 v77, 31, v76
	v_ashrrev_i32_e32 v79, 31, v78
	v_lshlrev_b32_e32 v2, 2, v71
	v_lshlrev_b32_e32 v6, 4, v61
	v_or_b32_e32 v113, 0x13c00, v2
	v_or_b32_e32 v114, 0x13d00, v2
	v_or_b32_e32 v115, 0x13c10, v2
	v_or_b32_e32 v116, 0x13d10, v2
	v_lshlrev_b64 v[2:3], 7, v[76:77]
	v_and_b32_e32 v10, 0x70, v6
	v_lshlrev_b64 v[6:7], 7, v[78:79]
	v_add_u32_e32 v1, 0x200, v61
	v_or_b32_e32 v2, v2, v10
	v_or_b32_e32 v6, v6, v10
	v_ashrrev_i32_e32 v80, 3, v1
	v_lshl_add_u64 v[2:3], s[52:53], 0, v[2:3]
	s_mov_b64 s[20:21], 0x73f0000
	v_lshl_add_u64 v[6:7], s[52:53], 0, v[6:7]
	v_ashrrev_i32_e32 v81, 31, v80
	v_lshl_add_u64 v[84:85], v[2:3], 0, s[20:21]
	v_lshl_add_u64 v[86:87], v[6:7], 0, s[20:21]
	s_mov_b64 s[20:21], 0x7430000
	v_add_u32_e32 v1, 0x300, v61
	v_lshl_add_u64 v[88:89], v[2:3], 0, s[20:21]
	v_lshlrev_b64 v[2:3], 7, v[80:81]
	v_ashrrev_i32_e32 v82, 3, v1
	v_or_b32_e32 v2, v2, v10
	v_ashrrev_i32_e32 v83, 31, v82
	v_lshl_add_u64 v[2:3], s[52:53], 0, v[2:3]
	v_lshl_add_u64 v[92:93], v[2:3], 0, s[20:21]
	v_lshlrev_b64 v[2:3], 7, v[82:83]
	s_movk_i32 s2, 0x90
	v_or_b32_e32 v2, v2, v10
	v_mul_lo_u32 v1, v76, s2
	v_mul_lo_u32 v5, v78, s2
	v_mul_lo_u32 v8, v80, s2
	v_mul_lo_u32 v9, v82, s2
	v_lshl_add_u64 v[2:3], s[52:53], 0, v[2:3]
	v_readlane_b32 s2, v254, 56
	s_cmpk_ge_i32 s2, 0x1e0
	s_cbranch_scc1 .Lperm_7
	s_and_b32 m0, s2, 7
	s_lshl_b32 m0, m0, 2
	s_bfe_u32 s98, s2, 0x20003
	s_add_i32 m0, m0, s98
	s_andn2_b32 s2, s2, 31
	s_or_b32 s2, s2, m0
.Lperm_7:
	s_mov_b32 s50, s65
	v_cmp_gt_u32_e32 vcc, 64, v61
	v_cmp_lt_u32_e64 s[4:5], 63, v61
	v_add_u32_e32 v67, 0xf400, v64
	v_add_u32_e32 v73, 0xf440, v64
	s_mov_b32 s3, 0
	v_cmp_eq_u32_e64 s[6:7], 0, v61
	v_or_b32_e32 v70, 16, v60
	v_or_b32_e32 v72, 32, v60
	v_or_b32_e32 v74, 48, v60
	v_cmp_eq_u32_e64 s[8:9], 0, v65
	v_cmp_gt_u32_e64 s[10:11], 2, v65
	v_cmp_gt_u32_e64 s[12:13], 4, v65
	v_cmp_gt_u32_e64 s[14:15], 8, v65
	v_cmp_gt_u32_e64 s[16:17], 16, v65
	v_cmp_gt_u32_e64 s[18:19], 32, v65
	v_lshl_add_u64 v[90:91], v[6:7], 0, s[20:21]
	v_lshl_add_u64 v[94:95], v[2:3], 0, s[20:21]
	s_mov_b32 s33, 0xbfb8aa3b
	s_mov_b32 s36, 0x3f2aaaab
	v_mov_b32_e32 v117, 0x3ecc95a3
	s_mov_b32 s37, 0x3f317218
	s_mov_b32 s38, 0x7f800000
	s_mov_b32 s39, 0x33800000
	v_mov_b32_e32 v118, 0x13cfc
	s_movk_i32 s42, 0x7fff
	v_mov_b32_e32 v96, 0x3f317218
	v_mov_b32_e32 v119, 0x7f800000
	v_mov_b32_e32 v120, 0x7fc00000
	v_mov_b32_e32 v121, 0xff800000
	v_mbcnt_hi_u32_b32 v122, -1, v191
	v_add_u32_e32 v123, v4, v1
	v_add_u32_e32 v124, v4, v5
	v_add_u32_e32 v125, v4, v8
	v_add_u32_e32 v126, v4, v9
	v_mov_b32_e32 v127, 1
	s_mov_b32 s43, s2
	s_mov_b32 s24, s2
	s_branch .LBB0_1509

.LBB0_1661:
	s_or_b64 exec, exec, s[0:1]
	s_add_u32 s0, s52, 0xdec4000
	s_addc_u32 s1, s53, 0
	v_writelane_b32 v254, s0, 18
	v_mov_b32_e32 v97, v190
	s_waitcnt lgkmcnt(0)
	v_writelane_b32 v254, s1, 19
	s_barrier
	v_readlane_b32 s0, v254, 56
	s_cmpk_ge_i32 s0, 0x1e0
	s_cbranch_scc1 .Lperm_8
	s_and_b32 m0, s0, 7
	s_lshl_b32 m0, m0, 2
	s_bfe_u32 s98, s0, 0x20003
	s_add_i32 m0, m0, s98
	s_andn2_b32 s0, s0, 31
	s_or_b32 s0, s0, m0
.Lperm_8:
	s_cmpk_gt_i32 s0, 0x2ff
	s_cbranch_scc1 .LBB0_1845
	v_lshlrev_b32_e32 v0, 3, v97
	v_and_b32_e32 v107, 56, v0
	v_mov_b32_e32 v0, 0
	v_and_b32_e32 v96, 15, v97
	v_lshlrev_b32_e32 v2, 1, v107
	v_mov_b32_e32 v3, v0
	v_lshl_add_u64 v[100:101], s[40:41], 0, v[2:3]
	v_mul_u32_u24_e32 v3, 0x48, v96
	v_lshlrev_b32_e32 v4, 1, v3
	v_and_b32_e32 v3, 48, v97
	v_and_b32_e32 v103, 63, v97
	v_ashrrev_i32_e32 v5, 6, v97
	v_add_u32_e32 v102, v3, v4
	s_movk_i32 s0, 0x1200
	v_mad_u64_u32 v[104:105], s[0:1], v5, s0, v[102:103]
	s_movk_i32 s0, 0x1100
	v_mul_u32_u24_e32 v10, 0x88, v96
	v_bfe_u32 v1, v97, 4, 2
	v_mul_lo_u32 v9, v5, s0
	v_lshlrev_b32_e32 v10, 1, v10
	v_lshlrev_b32_e32 v8, 2, v1
	v_add3_u32 v157, v9, v10, v3
	v_lshlrev_b32_e32 v9, 7, v96
	s_movk_i32 s0, 0x900
	v_lshlrev_b32_e32 v7, 5, v5
	v_lshlrev_b32_e32 v1, 3, v1
	v_lshlrev_b32_e32 v6, 2, v103
	v_add_u32_e32 v158, v102, v9
	v_and_b32_e32 v9, 0xffffffc0, v97
	v_lshl_or_b32 v163, v5, 4, v8
	v_mad_u64_u32 v[4:5], s[0:1], v5, s0, v[4:5]
	v_or_b32_e32 v98, v8, v7
	v_or_b32_e32 v111, 0x13c00, v6
	v_or_b32_e32 v151, 0x13d00, v6
	v_lshlrev_b32_e32 v6, 4, v96
	v_or_b32_e32 v10, v9, v1
	s_mov_b32 s0, 0x11800
	v_or_b32_e32 v1, v7, v1
	v_add_u32_e32 v7, 0x300, v97
	v_ashrrev_i32_e32 v165, 4, v97
	s_movk_i32 s3, 0x110
	v_add3_u32 v164, v4, v3, s0
	v_add_u32_e32 v4, 0x100, v97
	v_mad_u64_u32 v[120:121], s[0:1], v165, s3, v[6:7]
	v_ashrrev_i32_e32 v121, 4, v4
	v_add_u32_e32 v5, 0x200, v97
	v_mad_u64_u32 v[122:123], s[0:1], v121, s3, v[6:7]
	v_ashrrev_i32_e32 v116, 3, v5
	v_ashrrev_i32_e32 v123, 4, v5
	v_lshlrev_b32_e32 v5, 2, v96
	v_or_b32_e32 v106, 16, v96
	s_movk_i32 s2, 0x90
	v_mad_u64_u32 v[124:125], s[0:1], v123, s3, v[6:7]
	v_or_b32_e32 v166, 0x13c00, v5
	v_or_b32_e32 v167, 0x13d00, v5
	v_mov_b32_e32 v5, 0x13c00
	v_or_b32_e32 v170, 1, v163
	v_or_b32_e32 v172, 2, v163
	v_or_b32_e32 v174, 3, v163
	v_ashrrev_i32_e32 v125, 4, v7
	v_lshl_add_u32 v168, v163, 2, v5
	v_mul_lo_u32 v169, v163, s2
	v_lshl_add_u32 v171, v170, 2, v5
	v_lshl_add_u32 v173, v172, 2, v5
	v_lshl_add_u32 v175, v174, 2, v5
	v_lshlrev_b32_e32 v5, 2, v106
	v_or_b32_e32 v108, 32, v96
	v_ashrrev_i32_e32 v118, 3, v7
	v_mad_u64_u32 v[126:127], s[0:1], v125, s3, v[6:7]
	v_or_b32_e32 v176, 0x13c00, v5
	v_or_b32_e32 v177, 0x13d00, v5
	v_add_u32_e32 v5, 0x11800, v169
	v_lshlrev_b32_e32 v6, 1, v106
	v_add_u32_e32 v7, 0x11890, v169
	v_add_u32_e32 v18, 0x11920, v169
	v_add_u32_e32 v19, 0x119b0, v169
	v_or_b32_e32 v178, v5, v6
	v_add_u32_e32 v179, v7, v6
	v_add_u32_e32 v180, v18, v6
	v_add_u32_e32 v181, v19, v6
	v_lshlrev_b32_e32 v6, 2, v108
	v_or_b32_e32 v110, 48, v96
	v_or_b32_e32 v182, 0x13c00, v6
	v_or_b32_e32 v183, 0x13d00, v6
	v_lshlrev_b32_e32 v6, 1, v108
	v_add_u32_e32 v184, v5, v6
	v_add_u32_e32 v185, v7, v6
	v_add_u32_e32 v186, v18, v6
	v_add_u32_e32 v187, v19, v6
	v_lshlrev_b32_e32 v6, 2, v110
	v_or_b32_e32 v188, 0x13c00, v6
	v_or_b32_e32 v189, 0x13d00, v6
	v_lshlrev_b32_e32 v6, 1, v110
	v_add_u32_e32 v192, v5, v6
	v_lshlrev_b32_e32 v5, 2, v107
	v_ashrrev_i32_e32 v114, 3, v4
	v_or_b32_e32 v196, 0x13c00, v5
	v_or_b32_e32 v198, 0x13d00, v5
	v_or_b32_e32 v199, 0x13c10, v5
	v_or_b32_e32 v200, 0x13d10, v5
	v_mbcnt_hi_u32_b32 v5, -1, v191
	v_mul_lo_u32 v11, v114, s2
	v_add_u32_e32 v193, v7, v6
	v_and_b32_e32 v7, 64, v5
	v_add_u32_e32 v194, v18, v6
	v_add_u32_e32 v195, v19, v6
	v_add_u32_e32 v201, v2, v11
	v_xor_b32_e32 v6, 1, v5
	v_add_u32_e32 v11, 64, v7
	v_cmp_lt_i32_e32 vcc, v6, v11
	v_writelane_b32 v254, s16, 50
	s_add_u32 s80, s52, 0x22f0000
	v_cndmask_b32_e32 v6, v5, v6, vcc
	v_lshlrev_b32_e32 v202, 2, v6
	v_xor_b32_e32 v6, 2, v5
	v_cmp_lt_i32_e32 vcc, v6, v11
	v_writelane_b32 v254, s17, 51
	v_writelane_b32 v254, s65, 54
	v_cndmask_b32_e32 v6, v5, v6, vcc
	v_lshlrev_b32_e32 v203, 2, v6
	v_xor_b32_e32 v6, 4, v5
	v_cmp_lt_i32_e32 vcc, v6, v11
	v_readlane_b32 s56, v254, 34
	v_readlane_b32 s66, v254, 44
	v_cndmask_b32_e32 v6, v5, v6, vcc
	v_lshlrev_b32_e32 v204, 2, v6
	v_xor_b32_e32 v6, 8, v5
	v_cmp_lt_i32_e32 vcc, v6, v11
	v_readlane_b32 s67, v254, 45
	v_readlane_b32 s70, v254, 48
	v_cndmask_b32_e32 v6, v5, v6, vcc
	v_lshlrev_b32_e32 v205, 2, v6
	v_add_u32_e32 v6, -1, v5
	v_cmp_lt_i32_e32 vcc, v6, v7
	v_readlane_b32 s71, v254, 49
	s_addc_u32 s81, s53, 0
	v_cndmask_b32_e32 v6, v6, v5, vcc
	v_lshlrev_b32_e32 v206, 2, v6
	v_add_u32_e32 v6, -2, v5
	v_cmp_lt_i32_e32 vcc, v6, v7
	s_mov_b64 s[66:67], s[70:71]
	s_add_u32 s78, s66, 0x4b02800
	v_cndmask_b32_e32 v6, v6, v5, vcc
	v_lshlrev_b32_e32 v207, 2, v6
	v_add_u32_e32 v6, -4, v5
	v_cmp_lt_i32_e32 vcc, v6, v7
	s_addc_u32 s79, s67, 0
	s_add_u32 s0, s66, 0x418e800
	v_cndmask_b32_e32 v6, v6, v5, vcc
	v_lshlrev_b32_e32 v208, 2, v6
	v_add_u32_e32 v6, -8, v5
	v_cmp_lt_i32_e32 vcc, v6, v7
	s_addc_u32 s1, s67, 0
	v_ashrrev_i32_e32 v112, 3, v97
	v_cndmask_b32_e32 v6, v6, v5, vcc
	v_lshlrev_b32_e32 v209, 2, v6
	v_add_u32_e32 v6, -16, v5
	v_cmp_lt_i32_e32 vcc, v6, v7
	v_add_u32_e32 v8, 0x13c00, v9
	v_mul_lo_u32 v9, v112, s2
	v_cndmask_b32_e32 v6, v6, v5, vcc
	v_lshlrev_b32_e32 v210, 2, v6
	v_subrev_u32_e32 v6, 32, v5
	v_cmp_lt_i32_e32 vcc, v6, v7
	v_mov_b32_e32 v7, v0
	v_lshlrev_b32_e32 v4, 1, v96
	v_cndmask_b32_e32 v5, v6, v5, vcc
	v_lshlrev_b32_e32 v6, 9, v96
	v_lshl_add_u64 v[128:129], s[0:1], 0, v[6:7]
	v_lshlrev_b32_e32 v6, 9, v106
	v_lshl_add_u64 v[130:131], s[0:1], 0, v[6:7]
	v_lshlrev_b32_e32 v6, 9, v108
	v_mul_lo_u32 v12, v116, s2
	v_mul_lo_u32 v13, v118, s2
	v_mul_u32_u24_e32 v14, 0x110, v96
	v_or_b32_e32 v127, 0x11800, v4
	v_add_u32_e32 v15, 0x90, v169
	v_add_u32_e32 v16, 0x120, v169
	v_add_u32_e32 v17, 0x1b0, v169
	v_add_u32_e32 v197, v2, v9
	v_mul_u32_u24_e32 v9, 0x90, v96
	v_lshlrev_b32_e32 v211, 2, v5
	v_readlane_b32 s57, v254, 35
	v_readlane_b32 s58, v254, 36
	v_readlane_b32 s59, v254, 37
	v_readlane_b32 s60, v254, 38
	v_readlane_b32 s61, v254, 39
	v_lshl_add_u64 v[132:133], s[0:1], 0, v[6:7]
	v_lshlrev_b32_e32 v6, 9, v110
	v_mov_b32_e32 v5, v0
	v_cmp_gt_u32_e64 s[4:5], 64, v97
	v_add_u32_e32 v105, 0xf400, v102
	v_add_u32_e32 v109, 0xf440, v102
	v_lshlrev_b32_e32 v156, 3, v96
	v_add_u32_e32 v159, 0xf400, v158
	v_add_u32_e32 v160, 0xf440, v158
	v_add_u32_e32 v161, 0xf480, v158
	v_add_u32_e32 v162, 0xf4c0, v158
	s_mov_b32 s83, 0
	v_cmp_eq_u32_e64 s[6:7], 0, v96
	v_ashrrev_i32_e32 v99, 31, v98
	v_ashrrev_i32_e32 v113, 31, v112
	v_ashrrev_i32_e32 v115, 31, v114
	v_ashrrev_i32_e32 v117, 31, v116
	v_ashrrev_i32_e32 v119, 31, v118
	v_cmp_eq_u32_e64 s[8:9], 0, v103
	v_cmp_gt_u32_e64 s[10:11], 2, v103
	v_cmp_gt_u32_e64 s[12:13], 4, v103
	v_cmp_gt_u32_e64 s[14:15], 8, v103
	v_cmp_gt_u32_e64 s[16:17], 16, v103
	v_cmp_gt_u32_e64 s[18:19], 32, v103
	v_cmp_le_i32_e64 s[20:21], v96, v163
	v_cmp_le_i32_e64 s[22:23], v96, v170
	v_cmp_le_i32_e64 s[24:25], v96, v172
	v_cmp_le_i32_e64 s[26:27], v96, v174
	v_cmp_le_i32_e64 s[28:29], v106, v163
	v_cmp_le_i32_e64 s[30:31], v106, v170
	v_cmp_le_i32_e64 s[34:35], v106, v172
	v_cmp_le_i32_e64 s[36:37], v106, v174
	v_cmp_le_i32_e64 s[38:39], v108, v163
	v_cmp_le_i32_e64 s[40:41], v108, v170
	v_cmp_le_i32_e64 s[42:43], v108, v172
	v_cmp_le_i32_e64 s[44:45], v108, v174
	v_cmp_le_i32_e64 s[46:47], v110, v163
	v_cmp_le_i32_e64 s[48:49], v110, v170
	v_cmp_le_i32_e64 s[50:51], v110, v172
	v_cmp_le_i32_e64 s[52:53], v110, v174
	v_readlane_b32 s62, v254, 40
	v_readlane_b32 s63, v254, 41
	v_readlane_b32 s64, v254, 42
	v_readlane_b32 s65, v254, 43
	s_mov_b64 s[56:57], s[60:61]
	v_lshl_add_u64 v[134:135], s[0:1], 0, v[6:7]
	v_lshl_add_u64 v[136:137], s[94:95], 0, v[4:5]
	v_mov_b32_e32 v212, 0x3ecc95a3
	v_add_u32_e32 v213, v2, v12
	v_add_u32_e32 v214, v2, v13
	v_mov_b32_e32 v215, 0x13cfc
	s_movk_i32 s85, 0x7fff
	v_add_u32_e32 v216, v10, v14
	v_add_u32_e32 v217, v127, v15
	v_add_u32_e32 v218, v127, v16
	v_add_u32_e32 v219, v127, v17
	v_add_u32_e32 v220, v8, v3
	v_mov_b32_e32 v138, 0x3f317218
	v_mov_b32_e32 v221, 0x7f800000
	v_mov_b32_e32 v222, 0x7fc00000
	v_mov_b32_e32 v223, 0xff800000
	v_mov_b32_e32 v224, 1
	v_add_u32_e32 v225, v1, v9
	v_readlane_b32 s33, v254, 56
	s_cmpk_ge_i32 s33, 0x1e0
	s_cbranch_scc1 .Lperm_9
	s_and_b32 m0, s33, 7
	s_lshl_b32 m0, m0, 2
	s_bfe_u32 s98, s33, 0x20003
	s_add_i32 m0, m0, s98
	s_andn2_b32 s33, s33, 31
	s_or_b32 s33, s33, m0
.Lperm_9:
	v_readlane_b32 s68, v254, 46
	v_readlane_b32 s69, v254, 47
	s_mov_b64 s[58:59], s[62:63]
	s_mov_b64 s[60:61], s[64:65]
	s_branch .LBB0_1664

.LBB0_2235:
	s_or_b64 exec, exec, s[0:1]
	v_readlane_b32 s0, v255, 12
	v_readlane_b32 s1, v255, 13
	v_mov_b32_e32 v0, v190
	s_andn2_b64 vcc, exec, s[0:1]
	s_waitcnt lgkmcnt(0)
	s_barrier
	s_cbranch_vccnz .LBB0_2312
	v_lshlrev_b32_e32 v5, 3, v0
	v_and_b32_e32 v10, 56, v5
	v_readlane_b32 s0, v255, 6
	v_lshlrev_b32_e32 v116, 1, v10
	v_mov_b32_e32 v117, 0
	v_readlane_b32 s1, v255, 7
	v_and_b32_e32 v123, 15, v0
	v_bfe_u32 v1, v0, 4, 2
	v_lshl_add_u64 v[118:119], s[0:1], 0, v[116:117]
	v_readlane_b32 s0, v254, 60
	v_readlane_b32 s1, v254, 61
	v_mul_u32_u24_e32 v5, 0x48, v123
	v_lshlrev_b32_e32 v6, 4, v1
	v_ashrrev_i32_e32 v3, 6, v0
	v_lshl_add_u64 v[120:121], s[0:1], 0, v[116:117]
	v_lshl_add_u32 v122, v5, 1, v6
	s_movk_i32 s0, 0x1200
	v_lshlrev_b32_e32 v114, 5, v3
	v_lshlrev_b32_e32 v2, 2, v1
	v_mad_u64_u32 v[124:125], s[0:1], v3, s0, v[122:123]
	v_or_b32_e32 v4, v2, v114
	v_readlane_b32 s0, v255, 15
	v_add_u32_e32 v1, 0x100, v0
	v_ashrrev_i32_e32 v5, 31, v4
	v_readlane_b32 s1, v255, 16
	v_ashrrev_i32_e32 v130, 3, v0
	v_ashrrev_i32_e32 v132, 3, v1
	v_add_u32_e32 v1, 0x200, v0
	v_add_u32_e32 v0, 0x300, v0
	v_ashrrev_i32_e32 v115, 31, v114
	v_lshl_add_u64 v[128:129], v[4:5], 2, s[0:1]
	v_ashrrev_i32_e32 v134, 3, v1
	v_ashrrev_i32_e32 v136, 3, v0
	s_movk_i32 s0, 0x90
	v_lshl_add_u64 v[8:9], v[114:115], 2, s[84:85]
	v_mov_b32_e32 v7, v117
	v_mul_lo_u32 v0, v130, s0
	v_mul_lo_u32 v1, v132, s0
	v_mul_lo_u32 v3, v134, s0
	v_mul_lo_u32 v4, v136, s0
	s_add_u32 s16, s52, 0xd7d8000
	v_lshlrev_b32_e32 v138, 2, v2
	v_lshl_add_u64 v[126:127], v[8:9], 0, v[6:7]
	v_cmp_gt_u32_e32 vcc, 16, v10
	v_ashrrev_i32_e32 v131, 31, v130
	v_ashrrev_i32_e32 v133, 31, v132
	v_ashrrev_i32_e32 v135, 31, v134
	v_ashrrev_i32_e32 v137, 31, v136
	s_addc_u32 s17, s53, 0
	s_mov_b32 s1, 0
	v_mov_b32_e32 v140, v138
	v_mov_b32_e32 v141, v117
	v_add_u32_e32 v125, v116, v0
	v_add_u32_e32 v144, v116, v1
	v_add_u32_e32 v145, v116, v3
	v_add_u32_e32 v146, v116, v4
	s_mov_b32 s18, s64
	s_cmpk_ge_i32 s18, 0x1e0
	s_cbranch_scc1 .Lperm_4
	s_and_b32 m0, s18, 7
	s_lshl_b32 m0, m0, 2
	s_bfe_u32 s98, s18, 0x20003
	s_add_i32 m0, m0, s98
	s_andn2_b32 s18, s18, 31
	s_or_b32 s18, s18, m0

.LBB0_2365:
	s_or_b64 exec, exec, s[0:1]
	v_readlane_b32 s0, v255, 21
	v_readlane_b32 s1, v255, 22
	v_mov_b32_e32 v1, v190
	s_andn2_b64 vcc, exec, s[0:1]
	s_waitcnt lgkmcnt(0)
	s_barrier
	s_cbranch_vccnz .LBB0_2495
	v_lshlrev_b32_e32 v0, 3, v1
	v_and_b32_e32 v12, 56, v0
	v_mov_b32_e32 v0, 0
	v_readlane_b32 s0, v255, 6
	v_and_b32_e32 v124, 15, v1
	v_lshlrev_b32_e32 v4, 1, v12
	v_mov_b32_e32 v5, v0
	v_readlane_b32 s1, v255, 7
	v_bfe_u32 v3, v1, 4, 2
	v_ashrrev_i32_e32 v9, 6, v1
	v_lshl_add_u64 v[130:131], s[0:1], 0, v[4:5]
	v_readlane_b32 s0, v254, 60
	v_mul_u32_u24_e32 v6, 0x48, v124
	v_lshlrev_b32_e32 v126, 5, v9
	v_readlane_b32 s1, v254, 61
	v_lshlrev_b32_e32 v13, 1, v6
	v_lshlrev_b32_e32 v6, 4, v3
	v_lshl_add_u64 v[132:133], s[0:1], 0, v[4:5]
	v_ashrrev_i32_e32 v127, 31, v126
	v_add_u32_e32 v134, v6, v13
	s_movk_i32 s0, 0x1200
	v_mad_u64_u32 v[136:137], s[0:1], v9, s0, v[134:135]
	v_lshl_add_u64 v[10:11], v[126:127], 2, s[84:85]
	v_mov_b32_e32 v7, v0
	v_lshl_add_u64 v[138:139], v[10:11], 0, v[6:7]
	s_movk_i32 s0, 0x1100
	v_mul_u32_u24_e32 v7, 0x88, v124
	v_lshlrev_b32_e32 v2, 2, v3
	v_lshlrev_b32_e32 v5, 3, v3
	v_mul_lo_u32 v3, v9, s0
	v_lshlrev_b32_e32 v7, 1, v7
	s_movk_i32 s0, 0xffc0
	v_add3_u32 v135, v3, v7, v6
	v_and_or_b32 v3, v1, s0, v5
	s_movk_i32 s0, 0x900
	v_mul_lo_u32 v5, v9, s0
	v_ashrrev_i32_e32 v144, 3, v1
	s_movk_i32 s0, 0x90
	v_lshlrev_b32_e32 v8, 4, v124
	v_lshl_or_b32 v173, v9, 4, v2
	v_mul_lo_u32 v9, v144, s0
	v_ashrrev_i32_e32 v189, 4, v1
	s_movk_i32 s8, 0x110
	v_add3_u32 v184, v5, v13, v6
	v_add_u32_e32 v5, 0x100, v1
	v_mad_u64_u32 v[152:153], s[2:3], v189, s8, v[8:9]
	v_ashrrev_i32_e32 v153, 4, v5
	v_add_u32_e32 v6, 0x200, v1
	v_mad_u64_u32 v[154:155], s[2:3], v153, s8, v[8:9]
	v_ashrrev_i32_e32 v155, 4, v6
	v_add_u32_e32 v7, 0x300, v1
	v_mad_u64_u32 v[156:157], s[2:3], v155, s8, v[8:9]
	v_ashrrev_i32_e32 v157, 4, v7
	v_mad_u64_u32 v[158:159], s[2:3], v157, s8, v[8:9]
	v_ashrrev_i32_e32 v146, 3, v5
	v_or_b32_e32 v5, 16, v124
	v_or_b32_e32 v159, 1, v173
	v_or_b32_e32 v192, 2, v173
	v_or_b32_e32 v193, 3, v173
	v_or_b32_e32 v13, 48, v124
	v_cmp_gt_i32_e64 s[16:17], v5, v173
	v_cmp_gt_i32_e64 s[18:19], v5, v159
	v_cmp_gt_i32_e64 s[20:21], v5, v192
	v_cmp_gt_i32_e64 s[22:23], v5, v193
	v_mbcnt_hi_u32_b32 v5, -1, v191
	v_ashrrev_i32_e32 v150, 3, v7
	v_or_b32_e32 v7, 32, v124
	v_cmp_gt_i32_e64 s[34:35], v13, v173
	v_cmp_gt_i32_e64 s[36:37], v13, v159
	v_cmp_gt_i32_e64 s[38:39], v13, v192
	v_cmp_gt_i32_e64 s[40:41], v13, v193
	v_and_b32_e32 v13, 64, v5
	v_cmp_gt_i32_e64 s[24:25], v7, v173
	v_cmp_gt_i32_e64 s[26:27], v7, v159
	v_cmp_gt_i32_e64 s[28:29], v7, v192
	v_cmp_gt_i32_e64 s[30:31], v7, v193
	v_xor_b32_e32 v7, 1, v5
	v_add_u32_e32 v13, 64, v13
	v_cmp_lt_i32_e32 vcc, v7, v13
	v_or_b32_e32 v128, v2, v126
	v_ashrrev_i32_e32 v148, 3, v6
	v_cndmask_b32_e32 v7, v5, v7, vcc
	v_lshlrev_b32_e32 v194, 2, v7
	v_xor_b32_e32 v7, 2, v5
	v_cmp_lt_i32_e32 vcc, v7, v13
	v_mov_b32_e32 v6, 0x1100
	v_mov_b32_e32 v8, 0x2200
	v_cndmask_b32_e32 v7, v5, v7, vcc
	v_lshlrev_b32_e32 v195, 2, v7
	v_xor_b32_e32 v7, 4, v5
	v_cmp_lt_i32_e32 vcc, v7, v13
	v_mov_b32_e32 v14, 0x3300
	v_readlane_b32 s42, v255, 15
	v_cndmask_b32_e32 v7, v5, v7, vcc
	v_lshlrev_b32_e32 v196, 2, v7
	v_xor_b32_e32 v7, 8, v5
	v_or_b32_e32 v142, 16, v128
	v_cmp_gt_u32_e64 s[6:7], 16, v12
	v_mul_lo_u32 v10, v146, s0
	v_mul_lo_u32 v11, v148, s0
	v_mul_lo_u32 v12, v150, s0
	v_mul_u32_u24_e32 v1, 0x110, v124
	v_mad_u32_u24 v6, v124, s8, v6
	v_mad_u32_u24 v8, v124, s8, v8
	v_mad_u32_u24 v14, v124, s8, v14
	v_cmp_lt_i32_e32 vcc, v7, v13
	v_lshl_add_u32 v137, v124, 7, v134
	v_ashrrev_i32_e32 v129, 31, v128
	v_readlane_b32 s43, v255, 16
	v_ashrrev_i32_e32 v143, 31, v142
	v_lshlrev_b32_e32 v15, 1, v124
	v_mul_lo_u32 v16, v173, s0
	v_cndmask_b32_e32 v5, v5, v7, vcc
	v_lshlrev_b32_e32 v162, 2, v2
	v_add_u32_e32 v198, v4, v9
	v_add_u32_e32 v199, v4, v10
	v_add_u32_e32 v200, v4, v11
	v_add_u32_e32 v201, v4, v12
	v_add_u32_e32 v1, v3, v1
	v_add_u32_e32 v2, v3, v6
	v_add_u32_e32 v4, v3, v8
	v_add_u32_e32 v3, v3, v14
	v_lshlrev_b32_e32 v125, 3, v124
	v_add_u32_e32 v185, 0xf400, v137
	v_add_u32_e32 v186, 0xf440, v137
	v_add_u32_e32 v187, 0xf480, v137
	v_add_u32_e32 v188, 0xf4c0, v137
	s_mov_b32 s1, 0
	v_cmp_eq_u32_e64 s[4:5], 0, v124
	v_lshl_add_u64 v[140:141], v[128:129], 2, s[42:43]
	v_ashrrev_i32_e32 v145, 31, v144
	v_ashrrev_i32_e32 v147, 31, v146
	v_ashrrev_i32_e32 v149, 31, v148
	v_ashrrev_i32_e32 v151, 31, v150
	v_cmp_gt_i32_e64 s[8:9], v124, v173
	v_cmp_gt_i32_e64 s[10:11], v124, v159
	v_cmp_gt_i32_e64 s[12:13], v124, v192
	v_cmp_gt_i32_e64 s[14:15], v124, v193
	v_lshlrev_b32_e32 v197, 2, v5
	v_lshl_add_u64 v[160:161], v[142:143], 2, s[42:43]
	v_lshlrev_b32_e32 v164, 1, v124
	s_movk_i32 s33, 0x7fff
	v_add_u32_e32 v202, v15, v16
	v_mov_b32_e32 v203, 1
	v_add_u32_e32 v204, 0xf000, v1
	v_add_u32_e32 v205, 0xf000, v2
	v_add_u32_e32 v206, 0xf000, v4
	v_add_u32_e32 v207, 0xf000, v3
	s_mov_b32 s56, s64
	s_cmpk_ge_i32 s56, 0x1e0
	s_cbranch_scc1 .Lperm_5
	s_and_b32 m0, s56, 7
	s_lshl_b32 m0, m0, 2
	s_bfe_u32 s98, s56, 0x20003
	s_add_i32 m0, m0, s98
	s_andn2_b32 s56, s56, 31
	s_or_b32 s56, s56, m0
